# v24 plus phase_norm gate-weight staging: 16 loads per thread in flight together
# baseline (speedup 1.0000x reference)
; DI int tid_() { int t = threadIdx.x; asm volatile("" : "+v"(t)); return t; }
; DI void phase_norm(const float* X, const float* nw, bf16_t* H, const float* Wg, int ldw, int col0, float* GATE, lptr lds) {
;     const int tid = tid_(), wave = tid >> 6, lane = tid & 63;
;     if (Wg) { for (int i = tid; i < 1024 * 8; i += 512) lst<float>(lds, 32768 + ((i & 7) * 1024 + (i >> 3)) * 4, Wg[(size_t)(i >> 3) * ldw + col0 + (i & 7)]); }
; __global__ void __launch_bounds__(512) mega(Params p) {
;     ...
;         const bool even = !(L & 1); const int j = L >> 1;
;         const float* Xin = (L == 0) ? p.in[0] : X;
;         const float* Win = even ? (p.in[6] + (size_t)j * 1024 * EVEN_IN) : (p.in[17] + (size_t)j * 1024 * ODD_IN);
;         const int ldw = even ? EVEN_IN : ODD_IN; const int NIN = even ? PE : PO;
;         for (int rep1 = 0; rep1 < (PROBE == 5 ? 2 : 1); ++rep1) {
;         phase_norm(Xin, p.in[3] + L * 1024, H, Win, ldw, even ? 2048 : 4096, GATE, lds);
.LBB0_78:
	s_and_b32 s0, s56, 1
	s_bitcmp1_b32 s56, 0
	s_cselect_b64 s[92:93], -1, 0
	s_lshr_b32 s10, s56, 1
	s_cmp_eq_u32 s0, 0
	s_cselect_b64 s[54:55], -1, 0
	v_readlane_b32 s36, v252, 18
	s_and_b64 s[0:1], s[54:55], exec
	v_readlane_b32 s50, v252, 32
	v_readlane_b32 s51, v252, 33
	s_mov_b32 s0, 0x382000
	v_readlane_b32 s37, v252, 19
	v_readlane_b32 s38, v252, 20
	v_readlane_b32 s39, v252, 21
	v_readlane_b32 s40, v252, 22
	v_readlane_b32 s41, v252, 23
	v_readlane_b32 s42, v252, 24
	v_readlane_b32 s43, v252, 25
	v_readlane_b32 s44, v252, 26
	v_readlane_b32 s45, v252, 27
	v_readlane_b32 s46, v252, 28
	v_readlane_b32 s47, v252, 29
	v_readlane_b32 s48, v252, 30
	v_readlane_b32 s49, v252, 31
	s_mov_b64 s[66:67], s[50:51]
	s_cselect_b32 s2, s0, 0x402000
	s_mov_b64 s[64:65], s[48:49]
	s_mov_b64 s[62:63], s[46:47]
	s_mov_b64 s[60:61], s[44:45]
	v_readlane_b32 s36, v250, 21
	v_readlane_b32 s38, v250, 23
	v_readlane_b32 s39, v250, 24
	s_movk_i32 s3, 0xe08
	s_mul_i32 s82, s10, s2
	s_cselect_b32 s1, s65, s39
	s_cselect_b32 s0, s64, s38
	s_cselect_b32 s11, s3, 0x1008
	s_lshl_b64 s[2:3], s[82:83], 2
	s_add_u32 s20, s0, s2
	s_addc_u32 s21, s1, s3
	s_cmp_lg_u64 s[0:1], 0
	v_mov_b32_e32 v2, v194
	s_movk_i32 s0, 0x2000
	s_mov_b32 s70, s56
	s_cselect_b64 s[56:57], -1, 0
	v_writelane_b32 v252, s10, 51
	v_cmp_gt_i32_e32 vcc, s0, v2
	s_and_b64 s[2:3], s[56:57], vcc
	v_readlane_b32 s37, v250, 22
	v_readlane_b32 s40, v250, 25
	v_readlane_b32 s41, v250, 26
	v_readlane_b32 s42, v250, 27
	v_readlane_b32 s43, v250, 28
	v_readlane_b32 s44, v250, 29
	v_readlane_b32 s45, v250, 30
	v_readlane_b32 s46, v250, 31
	v_readlane_b32 s47, v250, 32
	v_readlane_b32 s48, v250, 33
	v_readlane_b32 s49, v250, 34
	v_readlane_b32 s50, v250, 35
	v_readlane_b32 s51, v250, 36
	s_and_saveexec_b64 s[0:1], s[2:3]
	v_readlane_b32 s66, v250, 37
	v_readlane_b32 s67, v250, 38
	s_cbranch_execz .LBB0_90
	s_and_b64 s[2:3], s[54:55], exec
	s_movk_i32 s2, 0x4000
	s_cselect_b32 s2, 0x2000, s2
	s_add_u32 s2, s20, s2
	v_and_b32_e32 v3, 7, v2
	s_addc_u32 s3, s21, 0
	v_lshlrev_b32_e32 v0, 2, v3
	v_lshl_add_u64 v[4:5], s[2:3], 0, v[0:1]
	v_lshl_add_u32 v0, v3, 12, 0
	v_ashrrev_i32_e32 v3, 3, v2
	v_mad_i64_i32 v[6:7], s[12:13], s11, v3, 0
	v_lshl_add_u64 v[6:7], v[6:7], 2, v[4:5]
	s_lshl_b32 s10, s11, 8
	v_mov_b32_e32 v8, s10
	v_mov_b32_e32 v9, 0
	v_lshl_add_u32 v10, v3, 2, v0
	global_load_dword v96, v[6:7], off
	v_lshl_add_u64 v[6:7], v[8:9], 0, v[6:7]
	global_load_dword v97, v[6:7], off
	v_lshl_add_u64 v[6:7], v[8:9], 0, v[6:7]
	global_load_dword v98, v[6:7], off
	v_lshl_add_u64 v[6:7], v[8:9], 0, v[6:7]
	global_load_dword v99, v[6:7], off
	v_lshl_add_u64 v[6:7], v[8:9], 0, v[6:7]
	global_load_dword v100, v[6:7], off
	v_lshl_add_u64 v[6:7], v[8:9], 0, v[6:7]
	global_load_dword v101, v[6:7], off
	v_lshl_add_u64 v[6:7], v[8:9], 0, v[6:7]
	global_load_dword v102, v[6:7], off
	v_lshl_add_u64 v[6:7], v[8:9], 0, v[6:7]
	global_load_dword v103, v[6:7], off
	v_lshl_add_u64 v[6:7], v[8:9], 0, v[6:7]
	global_load_dword v104, v[6:7], off
	v_lshl_add_u64 v[6:7], v[8:9], 0, v[6:7]
	global_load_dword v105, v[6:7], off
	v_lshl_add_u64 v[6:7], v[8:9], 0, v[6:7]
	global_load_dword v106, v[6:7], off
	v_lshl_add_u64 v[6:7], v[8:9], 0, v[6:7]
	global_load_dword v107, v[6:7], off
	v_lshl_add_u64 v[6:7], v[8:9], 0, v[6:7]
	global_load_dword v108, v[6:7], off
	v_lshl_add_u64 v[6:7], v[8:9], 0, v[6:7]
	global_load_dword v109, v[6:7], off
	v_lshl_add_u64 v[6:7], v[8:9], 0, v[6:7]
	global_load_dword v110, v[6:7], off
	v_lshl_add_u64 v[6:7], v[8:9], 0, v[6:7]
	global_load_dword v111, v[6:7], off
	s_waitcnt vmcnt(15)
	ds_write_b32 v10, v96 offset:32768
	s_waitcnt vmcnt(14)
	ds_write_b32 v10, v97 offset:33024
	s_waitcnt vmcnt(13)
	ds_write_b32 v10, v98 offset:33280
	s_waitcnt vmcnt(12)
	ds_write_b32 v10, v99 offset:33536
	s_waitcnt vmcnt(11)
	ds_write_b32 v10, v100 offset:33792
	s_waitcnt vmcnt(10)
	ds_write_b32 v10, v101 offset:34048
	s_waitcnt vmcnt(9)
	ds_write_b32 v10, v102 offset:34304
	s_waitcnt vmcnt(8)
	ds_write_b32 v10, v103 offset:34560
	s_waitcnt vmcnt(7)
	ds_write_b32 v10, v104 offset:34816
	s_waitcnt vmcnt(6)
	ds_write_b32 v10, v105 offset:35072
	s_waitcnt vmcnt(5)
	ds_write_b32 v10, v106 offset:35328
	s_waitcnt vmcnt(4)
	ds_write_b32 v10, v107 offset:35584
	s_waitcnt vmcnt(3)
	ds_write_b32 v10, v108 offset:35840
	s_waitcnt vmcnt(2)
	ds_write_b32 v10, v109 offset:36096
	s_waitcnt vmcnt(1)
	ds_write_b32 v10, v110 offset:36352
	s_waitcnt vmcnt(0)
	ds_write_b32 v10, v111 offset:36608
